# GEMM6: row statistics loaded at the top of each tile and the epilogue's in-order vmcnt waits dropped (second half no longer waits for the first half's stores)
# speedup vs baseline: 1.0793x; 1.0025x over previous
.LBB0_2101:
	s_lshl_b32 s0, s8, 8
	s_add_i32 s0, s0, s62
	v_or_b32_e32 v150, s0, v166
	v_ashrrev_i32_e32 v151, 31, v150
	v_lshl_add_u64 v[152:153], v[150:151], 2, s[16:17]
	v_mov_b32_e32 v138, v233
	v_or_b32_e32 v158, 16, v150
	v_or_b32_e32 v156, 32, v150
	v_or_b32_e32 v154, 48, v150
	v_ashrrev_i32_e32 v159, 31, v158
	v_ashrrev_i32_e32 v157, 31, v156
	v_ashrrev_i32_e32 v155, 31, v154
	v_lshl_add_u64 v[148:149], v[158:159], 2, s[16:17]
	v_lshl_add_u64 v[160:161], v[156:157], 2, s[16:17]
	v_lshl_add_u64 v[162:163], v[154:155], 2, s[16:17]
	v_mov_b32_e32 v157, v242
	v_mov_b32_e32 v155, v243
	v_mov_b32_e32 v151, v244
	v_lshl_or_b32 v148, s6, 8, v168
	v_mov_b64_e32 v[160:161], s[18:19]
	s_ashr_i32 s25, s0, 11
	v_add_u32_e32 v159, 0xffffc000, v150
	v_cmp_gt_i32_e64 s[6:7], s59, v150
	v_ashrrev_i32_e32 v149, 31, v148
	v_mov_b32_e32 v164, s25
	v_cndmask_b32_e64 v162, 7, v173, s[6:7]
	v_mad_i64_i32 v[160:161], s[0:1], v150, s70, v[160:161]
	v_lshrrev_b32_e32 v159, 3, v159
	v_and_b32_e32 v165, v162, v150
	v_cndmask_b32_e64 v183, -6, v174, s[6:7]
	v_cndmask_b32_e64 v184, 6, v175, s[6:7]
	v_cndmask_b32_e64 v188, v176, v177, s[6:7]
	v_lshl_add_u64 v[162:163], v[148:149], 1, v[160:161]
	v_cndmask_b32_e64 v159, v159, v164, s[6:7]
	v_lshlrev_b32_e32 v159, 1, v159
	v_add3_u32 v159, v165, v183, v159
	v_cmp_lt_i32_e32 vcc, s71, v148
	v_cmp_lt_u32_e64 s[8:9], v165, v184
	s_nor_b64 s[0:1], vcc, s[8:9]
	v_fmamk_f32 v138, v138, 0x3a800000, v172
	v_mul_f32_e32 v160, 0x4b800000, v138
	v_cmp_gt_f32_e64 s[6:7], s69, v138
	s_nop 1
	v_cndmask_b32_e64 v138, v138, v160, s[6:7]
	v_rsq_f32_e32 v138, v138
	v_mad_i64_i32 v[160:161], s[10:11], v159, s70, 0
	v_mul_f32_e32 v159, 0x45800000, v138
	v_cndmask_b32_e64 v164, v138, v159, s[6:7]
	v_pk_mul_f32 v[128:129], v[128:129], v[164:165] op_sel_hi:[1,0]
	v_pk_mul_f32 v[126:127], v[126:127], v[164:165] op_sel_hi:[1,0]
	v_pk_mul_f32 v[124:125], v[124:125], v[164:165] op_sel_hi:[1,0]
	v_pk_mul_f32 v[122:123], v[122:123], v[164:165] op_sel_hi:[1,0]
	v_lshlrev_b32_e32 v138, 2, v188
	v_cvt_pk_bf16_f32 v184, v126, v127
	v_cvt_pk_bf16_f32 v185, v128, v129
	v_cvt_pk_bf16_f32 v186, v122, v123
	v_cvt_pk_bf16_f32 v187, v124, v125
	global_store_dwordx4 v[162:163], v[184:187], off
	s_and_saveexec_b64 s[6:7], s[0:1]
	s_cbranch_execz .LBB0_2103
	v_lshl_add_u64 v[184:185], s[44:45], 0, v[138:139]
	v_lshl_add_u64 v[184:185], v[184:185], 0, v[160:161]
	v_lshl_add_u64 v[184:185], v[148:149], 2, v[184:185]
	global_store_dwordx4 v[184:185], v[126:129], off
	global_store_dwordx4 v[184:185], v[122:125], off offset:16

.LBB0_2117:
	s_or_b64 exec, exec, s[8:9]
	v_mov_b32_e32 v70, v245
	v_mov_b32_e32 v75, v246
	v_mov_b32_e32 v74, v247
	v_mov_b32_e32 v72, v248
	v_add_u32_e32 v68, 0x80, v150
	v_add_u32_e32 v69, 0xffffc080, v150
	v_cmp_gt_i32_e64 s[8:9], s72, v150
	v_mov_b64_e32 v[66:67], s[18:19]
	v_ashrrev_i32_e32 v73, 11, v68
	v_cndmask_b32_e64 v71, 7, v173, s[8:9]
	v_lshrrev_b32_e32 v69, 3, v69
	v_mad_i64_i32 v[66:67], s[0:1], v68, s70, v[66:67]
	v_and_b32_e32 v71, v71, v68
	v_cndmask_b32_e64 v78, v69, v73, s[8:9]
	v_lshl_add_u64 v[68:69], v[148:149], 1, v[66:67]
	v_cndmask_b32_e64 v76, -6, v174, s[8:9]
	v_cndmask_b32_e64 v77, 6, v175, s[8:9]
	v_lshlrev_b32_e32 v66, 1, v78
	v_cndmask_b32_e64 v80, v176, v177, s[8:9]
	v_cmp_lt_u32_e64 s[8:9], v71, v77
	v_add3_u32 v66, v71, v76, v66
	s_nor_b64 s[0:1], vcc, s[8:9]
	v_lshlrev_b32_e32 v138, 2, v80
	v_fmamk_f32 v67, v70, 0x3a800000, v172
	v_mul_f32_e32 v70, 0x4b800000, v67
	v_cmp_gt_f32_e64 s[10:11], s69, v67
	s_nop 1
	v_cndmask_b32_e64 v67, v67, v70, s[10:11]
	v_rsq_f32_e32 v70, v67
	v_mad_i64_i32 v[66:67], s[34:35], v66, s70, 0
	v_mul_f32_e32 v71, 0x45800000, v70
	v_cndmask_b32_e64 v70, v70, v71, s[10:11]
	v_pk_mul_f32 v[64:65], v[64:65], v[70:71] op_sel_hi:[1,0]
	v_pk_mul_f32 v[62:63], v[62:63], v[70:71] op_sel_hi:[1,0]
	v_pk_mul_f32 v[60:61], v[60:61], v[70:71] op_sel_hi:[1,0]
	v_pk_mul_f32 v[58:59], v[58:59], v[70:71] op_sel_hi:[1,0]
	v_cvt_pk_bf16_f32 v76, v62, v63
	v_cvt_pk_bf16_f32 v77, v64, v65
	v_cvt_pk_bf16_f32 v79, v60, v61
	s_nop 0
	v_cvt_pk_bf16_f32 v78, v58, v59
	global_store_dwordx4 v[68:69], v[76:79], off
	s_and_saveexec_b64 s[10:11], s[0:1]
	s_cbranch_execz .LBB0_2119
	v_lshl_add_u64 v[76:77], s[44:45], 0, v[138:139]
	v_lshl_add_u64 v[76:77], v[76:77], 0, v[66:67]
	v_lshl_add_u64 v[76:77], v[148:149], 2, v[76:77]
	global_store_dwordx4 v[76:77], v[62:65], off
	global_store_dwordx4 v[76:77], v[58:61], off offset:16

.LBB0_2121:
	s_or_b64 exec, exec, s[8:9]
	v_fmamk_f32 v51, v75, 0x3a800000, v172
	v_mul_f32_e32 v52, 0x4b800000, v51
	v_cmp_gt_f32_e64 s[8:9], s69, v51
	v_add_u32_e32 v50, 0xffffc090, v150
	v_cmp_gt_i32_e64 s[10:11], s73, v150
	v_cndmask_b32_e64 v51, v51, v52, s[8:9]
	v_rsq_f32_e32 v51, v51
	v_add_u32_e32 v53, 0x90, v150
	v_lshrrev_b32_e32 v50, 3, v50
	v_cndmask_b32_e64 v52, 7, v180, s[10:11]
	v_cndmask_b32_e64 v50, v50, v73, s[10:11]
	v_and_b32_e32 v54, v52, v53
	v_mul_f32_e32 v52, 0x45800000, v51
	v_cndmask_b32_e64 v52, v51, v52, s[8:9]
	v_cndmask_b32_e64 v51, -6, v174, s[10:11]
	v_cndmask_b32_e64 v55, 6, v175, s[10:11]
	v_lshlrev_b32_e32 v50, 1, v50
	v_cmp_lt_u32_e64 s[8:9], v54, v55
	v_add3_u32 v50, v54, v51, v50
	v_mov_b64_e32 v[54:55], s[18:19]
	v_cndmask_b32_e64 v60, v176, v177, s[10:11]
	v_mad_i64_i32 v[50:51], s[0:1], v50, s70, 0
	v_mad_i64_i32 v[54:55], s[0:1], v53, s70, v[54:55]
	v_pk_mul_f32 v[48:49], v[48:49], v[52:53] op_sel_hi:[1,0]
	v_pk_mul_f32 v[46:47], v[46:47], v[52:53] op_sel_hi:[1,0]
	v_pk_mul_f32 v[44:45], v[44:45], v[52:53] op_sel_hi:[1,0]
	v_pk_mul_f32 v[42:43], v[42:43], v[52:53] op_sel_hi:[1,0]
	v_lshl_add_u64 v[54:55], v[148:149], 1, v[54:55]
	s_nor_b64 s[0:1], vcc, s[8:9]
	v_lshlrev_b32_e32 v138, 2, v60
	v_cvt_pk_bf16_f32 v56, v46, v47
	v_cvt_pk_bf16_f32 v57, v48, v49
	v_cvt_pk_bf16_f32 v58, v42, v43
	v_cvt_pk_bf16_f32 v59, v44, v45
	global_store_dwordx4 v[54:55], v[56:59], off
	s_and_saveexec_b64 s[10:11], s[0:1]
	s_cbranch_execz .LBB0_2123
	v_lshl_add_u64 v[56:57], s[44:45], 0, v[138:139]
	v_lshl_add_u64 v[56:57], v[56:57], 0, v[50:51]
	v_lshl_add_u64 v[56:57], v[148:149], 2, v[56:57]
	global_store_dwordx4 v[56:57], v[46:49], off
	global_store_dwordx4 v[56:57], v[42:45], off offset:16

.LBB0_2125:
	s_or_b64 exec, exec, s[8:9]
	v_fmamk_f32 v35, v74, 0x3a800000, v172
	v_mul_f32_e32 v36, 0x4b800000, v35
	v_cmp_gt_f32_e64 s[8:9], s69, v35
	v_add_u32_e32 v34, 0xffffc0a0, v150
	v_cmp_gt_i32_e64 s[10:11], s74, v150
	v_cndmask_b32_e64 v35, v35, v36, s[8:9]
	v_rsq_f32_e32 v35, v35
	v_add_u32_e32 v37, 0xa0, v150
	v_lshrrev_b32_e32 v34, 3, v34
	v_cndmask_b32_e64 v36, 7, v181, s[10:11]
	v_cndmask_b32_e64 v34, v34, v73, s[10:11]
	v_and_b32_e32 v38, v36, v37
	v_mul_f32_e32 v36, 0x45800000, v35
	v_cndmask_b32_e64 v36, v35, v36, s[8:9]
	v_cndmask_b32_e64 v35, -6, v174, s[10:11]
	v_cndmask_b32_e64 v39, 6, v175, s[10:11]
	v_lshlrev_b32_e32 v34, 1, v34
	v_cmp_lt_u32_e64 s[8:9], v38, v39
	v_add3_u32 v34, v38, v35, v34
	v_mov_b64_e32 v[38:39], s[18:19]
	v_cndmask_b32_e64 v44, v176, v177, s[10:11]
	v_mad_i64_i32 v[34:35], s[0:1], v34, s70, 0
	v_mad_i64_i32 v[38:39], s[0:1], v37, s70, v[38:39]
	v_pk_mul_f32 v[32:33], v[32:33], v[36:37] op_sel_hi:[1,0]
	v_pk_mul_f32 v[30:31], v[30:31], v[36:37] op_sel_hi:[1,0]
	v_pk_mul_f32 v[28:29], v[28:29], v[36:37] op_sel_hi:[1,0]
	v_pk_mul_f32 v[26:27], v[26:27], v[36:37] op_sel_hi:[1,0]
	v_lshl_add_u64 v[38:39], v[148:149], 1, v[38:39]
	s_nor_b64 s[0:1], vcc, s[8:9]
	v_lshlrev_b32_e32 v138, 2, v44
	v_cvt_pk_bf16_f32 v40, v30, v31
	v_cvt_pk_bf16_f32 v41, v32, v33
	v_cvt_pk_bf16_f32 v42, v26, v27
	v_cvt_pk_bf16_f32 v43, v28, v29
	global_store_dwordx4 v[38:39], v[40:43], off
	s_and_saveexec_b64 s[10:11], s[0:1]
	s_cbranch_execz .LBB0_2127
	v_lshl_add_u64 v[40:41], s[44:45], 0, v[138:139]
	v_lshl_add_u64 v[40:41], v[40:41], 0, v[34:35]
	v_lshl_add_u64 v[40:41], v[148:149], 2, v[40:41]
	global_store_dwordx4 v[40:41], v[30:33], off
	global_store_dwordx4 v[40:41], v[26:29], off offset:16

.LBB0_2129:
	s_or_b64 exec, exec, s[8:9]
	v_fmamk_f32 v19, v72, 0x3a800000, v172
	v_mul_f32_e32 v20, 0x4b800000, v19
	v_cmp_gt_f32_e64 s[8:9], s69, v19
	v_add_u32_e32 v18, 0xffffc0b0, v150
	v_cmp_gt_i32_e64 s[10:11], s75, v150
	v_cndmask_b32_e64 v19, v19, v20, s[8:9]
	v_rsq_f32_e32 v19, v19
	v_add_u32_e32 v21, 0xb0, v150
	v_lshrrev_b32_e32 v18, 3, v18
	v_cndmask_b32_e64 v20, 7, v182, s[10:11]
	v_cndmask_b32_e64 v18, v18, v73, s[10:11]
	v_and_b32_e32 v22, v20, v21
	v_mul_f32_e32 v20, 0x45800000, v19
	v_cndmask_b32_e64 v20, v19, v20, s[8:9]
	v_cndmask_b32_e64 v19, -6, v174, s[10:11]
	v_cndmask_b32_e64 v23, 6, v175, s[10:11]
	v_lshlrev_b32_e32 v18, 1, v18
	v_cmp_lt_u32_e64 s[8:9], v22, v23
	v_add3_u32 v18, v22, v19, v18
	v_mov_b64_e32 v[22:23], s[18:19]
	v_cndmask_b32_e64 v28, v176, v177, s[10:11]
	v_mad_i64_i32 v[18:19], s[0:1], v18, s70, 0
	v_mad_i64_i32 v[22:23], s[0:1], v21, s70, v[22:23]
	v_pk_mul_f32 v[16:17], v[16:17], v[20:21] op_sel_hi:[1,0]
	v_pk_mul_f32 v[14:15], v[14:15], v[20:21] op_sel_hi:[1,0]
	v_pk_mul_f32 v[12:13], v[12:13], v[20:21] op_sel_hi:[1,0]
	v_pk_mul_f32 v[10:11], v[10:11], v[20:21] op_sel_hi:[1,0]
	v_lshl_add_u64 v[22:23], v[148:149], 1, v[22:23]
	s_nor_b64 s[0:1], vcc, s[8:9]
	v_lshlrev_b32_e32 v138, 2, v28
	v_cvt_pk_bf16_f32 v24, v14, v15
	v_cvt_pk_bf16_f32 v25, v16, v17
	v_cvt_pk_bf16_f32 v26, v10, v11
	v_cvt_pk_bf16_f32 v27, v12, v13
	global_store_dwordx4 v[22:23], v[24:27], off
	s_and_saveexec_b64 s[10:11], s[0:1]
	s_cbranch_execz .LBB0_2131
	v_lshl_add_u64 v[24:25], s[44:45], 0, v[138:139]
	v_lshl_add_u64 v[24:25], v[24:25], 0, v[18:19]
	v_lshl_add_u64 v[24:25], v[148:149], 2, v[24:25]
	global_store_dwordx4 v[24:25], v[14:17], off
	global_store_dwordx4 v[24:25], v[10:13], off offset:16
